# differential attention: V^T fragment reads moved up to right after the QK MFMAs (into the MFMA-result wait shadow), 3 bodies (on v100)
# speedup vs baseline: 1.0089x; 1.0012x over previous
.LBB0_311:
	ds_read_b128 v[6:9], v4 offset:12288
	ds_read_b128 v[10:13], v5 offset:12288
	ds_read_b128 v[132:135], v2 offset:12288
	ds_read_b128 v[136:139], v3 offset:12288
	s_add_i32 s8, s58, 0x7f
	s_cmp_gt_i32 s8, s54
	s_mov_b64 s[8:9], -1
	s_waitcnt lgkmcnt(3)
	v_mfma_f32_32x32x16_bf16 v[96:111], v[6:9], v[116:119], 0
	s_waitcnt lgkmcnt(2)
	v_mfma_f32_32x32x16_bf16 v[96:111], v[10:13], v[120:123], v[96:111]
	s_waitcnt lgkmcnt(1)
	v_mfma_f32_32x32x16_bf16 v[96:111], v[132:135], v[124:127], v[96:111]
	s_waitcnt lgkmcnt(0)
	v_mfma_f32_32x32x16_bf16 v[96:111], v[136:139], v[128:131], v[96:111]
	v_add_u32_e32 v206, v1, v236
	v_add_u32_e32 v207, v1, v237
	ds_read_b128 v[132:135], v206 offset:32768
	ds_read_b128 v[136:139], v207 offset:32768
	ds_read_b128 v[140:143], v206 offset:40960
	ds_read_b128 v[144:147], v207 offset:40960
	ds_read_b128 v[148:151], v206 offset:49152
	ds_read_b128 v[152:155], v207 offset:49152
	ds_read_b128 v[156:159], v206 offset:57344
	ds_read_b128 v[160:163], v207 offset:57344
	s_cbranch_scc1 .LBB0_313
	s_nop 10
	v_fmamk_f32 v80, v96, 0x3e38aa3b, v216
	v_fma_f32 v81, v97, s30, -v214
	v_fmamk_f32 v82, v98, 0x3e38aa3b, v217
	v_max3_f32 v7, v80, s52, v81
	v_fmamk_f32 v83, v99, 0x3e38aa3b, v218
	v_add_u32_e32 v6, s58, v188
	v_fmamk_f32 v84, v100, 0x3e38aa3b, v219
	v_max3_f32 v7, v7, v82, v83
	v_fmamk_f32 v85, v101, 0x3e38aa3b, v220
	v_add_u32_e32 v6, 0x60, v6
	v_fmamk_f32 v86, v102, 0x3e38aa3b, v221
	v_max3_f32 v7, v7, v84, v85
	v_fmamk_f32 v87, v103, 0x3e38aa3b, v222
	v_cvt_f32_i32_e32 v6, v6
	v_fmamk_f32 v88, v104, 0x3e38aa3b, v223
	v_max3_f32 v7, v7, v86, v87
	v_fmamk_f32 v89, v105, 0x3e38aa3b, v224
	v_fmamk_f32 v90, v106, 0x3e38aa3b, v225
	v_max3_f32 v7, v7, v88, v89
	v_fmamk_f32 v91, v107, 0x3e38aa3b, v226
	v_fmamk_f32 v92, v108, 0x3e38aa3b, v227
	v_max3_f32 v7, v7, v90, v91
	v_fmamk_f32 v93, v109, 0x3e38aa3b, v228
	v_fmamk_f32 v94, v110, 0x3e38aa3b, v229
	v_max3_f32 v7, v7, v92, v93
	v_fmamk_f32 v95, v111, 0x3e38aa3b, v230
	v_mul_f32_e64 v6, -v214, v6
	v_max3_f32 v7, v7, v94, v95
	s_mov_b64 s[8:9], 0

.LBB0_333:
	v_sub_f32_e32 v6, v246, v6
	v_sub_f32_e32 v7, v80, v6
	v_exp_f32_e32 v7, v7
	v_sub_f32_e32 v9, v81, v6
	v_exp_f32_e32 v9, v9
	v_sub_f32_e32 v10, v82, v6
	v_exp_f32_e32 v10, v10
	v_sub_f32_e32 v11, v83, v6
	v_exp_f32_e32 v11, v11
	v_sub_f32_e32 v12, v84, v6
	v_add_f32_e32 v8, 0, v7
	v_exp_f32_e32 v12, v12
	v_sub_f32_e32 v13, v85, v6
	v_add_f32_e32 v8, v9, v8
	v_exp_f32_e32 v13, v13
	v_sub_f32_e32 v14, v86, v6
	v_add_f32_e32 v8, v10, v8
	v_exp_f32_e32 v14, v14
	v_sub_f32_e32 v15, v87, v6
	v_add_f32_e32 v8, v11, v8
	v_exp_f32_e32 v15, v15
	v_sub_f32_e32 v80, v88, v6
	v_add_f32_e32 v8, v12, v8
	v_exp_f32_e32 v80, v80
	v_sub_f32_e32 v81, v89, v6
	v_add_f32_e32 v8, v13, v8
	v_exp_f32_e32 v81, v81
	v_sub_f32_e32 v82, v90, v6
	v_add_f32_e32 v8, v14, v8
	v_exp_f32_e32 v82, v82
	v_sub_f32_e32 v83, v91, v6
	v_add_f32_e32 v8, v15, v8
	v_exp_f32_e32 v83, v83
	v_add_f32_e32 v8, v80, v8
	v_add_f32_e32 v8, v81, v8
	v_sub_f32_e32 v84, v92, v6
	v_sub_f32_e32 v85, v93, v6
	v_sub_f32_e32 v86, v94, v6
	v_sub_f32_e32 v6, v95, v6
	v_add_f32_e32 v8, v82, v8
	v_exp_f32_e32 v87, v6
	v_cvt_pk_bf16_f32 v6, v7, v9
	v_cvt_pk_bf16_f32 v9, v14, v15
	v_add_f32_e32 v8, v83, v8
	v_cvt_pk_bf16_f32 v7, v10, v11
	v_cvt_pk_bf16_f32 v10, v80, v81
	v_cvt_pk_bf16_f32 v11, v82, v83
	v_exp_f32_e32 v84, v84
	v_exp_f32_e32 v85, v85
	v_exp_f32_e32 v86, v86
	v_add_f32_e32 v8, v84, v8
	v_add_f32_e32 v8, v85, v8
	v_add_f32_e32 v8, v86, v8
	v_add_f32_e32 v88, v87, v8
	v_cvt_pk_bf16_f32 v8, v12, v13
	v_cvt_pk_bf16_f32 v12, v84, v85
	v_cvt_pk_bf16_f32 v13, v86, v87
	s_waitcnt lgkmcnt(7)
	v_mfma_f32_32x32x16_bf16 v[64:79], v[132:135], v[6:9], v[64:79]
	v_add_f32_e32 v245, v245, v88
	s_waitcnt lgkmcnt(6)
	v_mfma_f32_32x32x16_bf16 v[64:79], v[136:139], v[10:13], v[64:79]
	s_waitcnt lgkmcnt(5)
	v_mfma_f32_32x32x16_bf16 v[48:63], v[140:143], v[6:9], v[48:63]
	s_waitcnt lgkmcnt(4)
	v_mfma_f32_32x32x16_bf16 v[48:63], v[144:147], v[10:13], v[48:63]
	s_waitcnt lgkmcnt(3)
	v_mfma_f32_32x32x16_bf16 v[32:47], v[148:151], v[6:9], v[32:47]
	s_waitcnt lgkmcnt(2)
	v_mfma_f32_32x32x16_bf16 v[32:47], v[152:155], v[10:13], v[32:47]
	s_waitcnt lgkmcnt(1)
	v_mfma_f32_32x32x16_bf16 v[16:31], v[156:159], v[6:9], v[16:31]
	s_waitcnt lgkmcnt(0)
	v_mfma_f32_32x32x16_bf16 v[16:31], v[160:163], v[10:13], v[16:31]
	s_add_i32 s8, s59, 2
	s_cmp_gt_u32 s8, s55
	s_cbranch_scc1 .LBB0_307
.LBB0_334:
	ds_read_b128 v[6:9], v4 offset:8192
	ds_read_b128 v[10:13], v5 offset:8192
	ds_read_b128 v[132:135], v2 offset:8192
	ds_read_b128 v[136:139], v3 offset:8192
	s_add_i32 s8, s58, 0x5f
	s_cmp_gt_i32 s8, s54
	s_mov_b64 s[8:9], -1
	s_waitcnt lgkmcnt(3)
	v_mfma_f32_32x32x16_bf16 v[96:111], v[6:9], v[116:119], 0
	s_waitcnt lgkmcnt(2)
	v_mfma_f32_32x32x16_bf16 v[96:111], v[10:13], v[120:123], v[96:111]
	s_waitcnt lgkmcnt(1)
	v_mfma_f32_32x32x16_bf16 v[96:111], v[132:135], v[124:127], v[96:111]
	s_waitcnt lgkmcnt(0)
	v_mfma_f32_32x32x16_bf16 v[96:111], v[136:139], v[128:131], v[96:111]
	v_add_u32_e32 v206, v1, v238
	v_add_u32_e32 v207, v1, v239
	ds_read_b128 v[132:135], v206 offset:32768
	ds_read_b128 v[136:139], v207 offset:32768
	ds_read_b128 v[140:143], v206 offset:40960
	ds_read_b128 v[144:147], v207 offset:40960
	ds_read_b128 v[148:151], v206 offset:49152
	ds_read_b128 v[152:155], v207 offset:49152
	ds_read_b128 v[156:159], v206 offset:57344
	ds_read_b128 v[160:163], v207 offset:57344
	s_cbranch_scc1 .LBB0_336
	s_nop 10
	v_fmamk_f32 v80, v96, 0x3e38aa3b, v216
	v_fma_f32 v81, v97, s30, -v214
	v_fmamk_f32 v82, v98, 0x3e38aa3b, v217
	v_max3_f32 v7, v80, s52, v81
	v_fmamk_f32 v83, v99, 0x3e38aa3b, v218
	v_fmamk_f32 v84, v100, 0x3e38aa3b, v219
	v_max3_f32 v7, v7, v82, v83
	v_fmamk_f32 v85, v101, 0x3e38aa3b, v220
	v_add3_u32 v6, v188, s58, 64
	v_fmamk_f32 v86, v102, 0x3e38aa3b, v221
	v_max3_f32 v7, v7, v84, v85
	v_fmamk_f32 v87, v103, 0x3e38aa3b, v222
	v_cvt_f32_i32_e32 v6, v6
	v_fmamk_f32 v88, v104, 0x3e38aa3b, v223
	v_max3_f32 v7, v7, v86, v87
	v_fmamk_f32 v89, v105, 0x3e38aa3b, v224
	v_fmamk_f32 v90, v106, 0x3e38aa3b, v225
	v_max3_f32 v7, v7, v88, v89
	v_fmamk_f32 v91, v107, 0x3e38aa3b, v226
	v_fmamk_f32 v92, v108, 0x3e38aa3b, v227
	v_max3_f32 v7, v7, v90, v91
	v_fmamk_f32 v93, v109, 0x3e38aa3b, v228
	v_fmamk_f32 v94, v110, 0x3e38aa3b, v229
	v_max3_f32 v7, v7, v92, v93
	v_fmamk_f32 v95, v111, 0x3e38aa3b, v230
	v_mul_f32_e64 v6, -v214, v6
	v_max3_f32 v7, v7, v94, v95
	s_mov_b64 s[8:9], 0

.LBB0_356:
	v_sub_f32_e32 v6, v246, v6
	v_sub_f32_e32 v7, v80, v6
	v_exp_f32_e32 v7, v7
	v_sub_f32_e32 v9, v81, v6
	v_exp_f32_e32 v9, v9
	v_sub_f32_e32 v10, v82, v6
	v_exp_f32_e32 v10, v10
	v_sub_f32_e32 v11, v83, v6
	v_exp_f32_e32 v11, v11
	v_sub_f32_e32 v12, v84, v6
	v_add_f32_e32 v8, 0, v7
	v_exp_f32_e32 v12, v12
	v_sub_f32_e32 v13, v85, v6
	v_add_f32_e32 v8, v9, v8
	v_exp_f32_e32 v13, v13
	v_sub_f32_e32 v14, v86, v6
	v_add_f32_e32 v8, v10, v8
	v_exp_f32_e32 v14, v14
	v_sub_f32_e32 v15, v87, v6
	v_add_f32_e32 v8, v11, v8
	v_exp_f32_e32 v15, v15
	v_sub_f32_e32 v80, v88, v6
	v_add_f32_e32 v8, v12, v8
	v_exp_f32_e32 v80, v80
	v_sub_f32_e32 v81, v89, v6
	v_add_f32_e32 v8, v13, v8
	v_exp_f32_e32 v81, v81
	v_sub_f32_e32 v82, v90, v6
	v_add_f32_e32 v8, v14, v8
	v_exp_f32_e32 v82, v82
	v_sub_f32_e32 v83, v91, v6
	v_add_f32_e32 v8, v15, v8
	v_exp_f32_e32 v83, v83
	v_add_f32_e32 v8, v80, v8
	v_add_f32_e32 v8, v81, v8
	v_sub_f32_e32 v84, v92, v6
	v_sub_f32_e32 v85, v93, v6
	v_sub_f32_e32 v86, v94, v6
	v_sub_f32_e32 v6, v95, v6
	v_add_f32_e32 v8, v82, v8
	v_exp_f32_e32 v87, v6
	v_cvt_pk_bf16_f32 v6, v7, v9
	v_cvt_pk_bf16_f32 v9, v14, v15
	v_add_f32_e32 v8, v83, v8
	v_cvt_pk_bf16_f32 v7, v10, v11
	v_cvt_pk_bf16_f32 v10, v80, v81
	v_cvt_pk_bf16_f32 v11, v82, v83
	v_exp_f32_e32 v84, v84
	v_exp_f32_e32 v85, v85
	v_exp_f32_e32 v86, v86
	v_add_f32_e32 v8, v84, v8
	v_add_f32_e32 v8, v85, v8
	v_add_f32_e32 v8, v86, v8
	v_add_f32_e32 v88, v87, v8
	v_cvt_pk_bf16_f32 v8, v12, v13
	v_cvt_pk_bf16_f32 v12, v84, v85
	v_cvt_pk_bf16_f32 v13, v86, v87
	s_waitcnt lgkmcnt(7)
	v_mfma_f32_32x32x16_bf16 v[64:79], v[132:135], v[6:9], v[64:79]
	v_add_f32_e32 v245, v245, v88
	s_waitcnt lgkmcnt(6)
	v_mfma_f32_32x32x16_bf16 v[64:79], v[136:139], v[10:13], v[64:79]
	s_waitcnt lgkmcnt(5)
	v_mfma_f32_32x32x16_bf16 v[48:63], v[140:143], v[6:9], v[48:63]
	s_waitcnt lgkmcnt(4)
	v_mfma_f32_32x32x16_bf16 v[48:63], v[144:147], v[10:13], v[48:63]
	s_waitcnt lgkmcnt(3)
	v_mfma_f32_32x32x16_bf16 v[32:47], v[148:151], v[6:9], v[32:47]
	s_waitcnt lgkmcnt(2)
	v_mfma_f32_32x32x16_bf16 v[32:47], v[152:155], v[10:13], v[32:47]
	s_waitcnt lgkmcnt(1)
	v_mfma_f32_32x32x16_bf16 v[16:31], v[156:159], v[6:9], v[16:31]
	s_waitcnt lgkmcnt(0)
	v_mfma_f32_32x32x16_bf16 v[16:31], v[160:163], v[10:13], v[16:31]
	s_cmp_ge_u32 s59, s55
	s_cbranch_scc1 .LBB0_308
.LBB0_357:
	ds_read_b128 v[6:9], v4 offset:4096
	ds_read_b128 v[10:13], v5 offset:4096
	ds_read_b128 v[132:135], v2 offset:4096
	ds_read_b128 v[136:139], v3 offset:4096
	s_add_i32 s8, s58, 63
	s_cmp_gt_i32 s8, s54
	s_mov_b64 s[8:9], -1
	s_waitcnt lgkmcnt(3)
	v_mfma_f32_32x32x16_bf16 v[96:111], v[6:9], v[116:119], 0
	s_waitcnt lgkmcnt(2)
	v_mfma_f32_32x32x16_bf16 v[96:111], v[10:13], v[120:123], v[96:111]
	s_waitcnt lgkmcnt(1)
	v_mfma_f32_32x32x16_bf16 v[96:111], v[132:135], v[124:127], v[96:111]
	s_waitcnt lgkmcnt(0)
	v_mfma_f32_32x32x16_bf16 v[96:111], v[136:139], v[128:131], v[96:111]
	v_add_u32_e32 v206, v1, v240
	v_add_u32_e32 v207, v1, v241
	ds_read_b128 v[132:135], v206 offset:32768
	ds_read_b128 v[136:139], v207 offset:32768
	ds_read_b128 v[140:143], v206 offset:40960
	ds_read_b128 v[144:147], v207 offset:40960
	ds_read_b128 v[148:151], v206 offset:49152
	ds_read_b128 v[152:155], v207 offset:49152
	ds_read_b128 v[156:159], v206 offset:57344
	ds_read_b128 v[160:163], v207 offset:57344
	s_cbranch_scc1 .LBB0_359
	s_nop 10
	v_fmamk_f32 v80, v96, 0x3e38aa3b, v216
	v_fma_f32 v81, v97, s30, -v214
	v_fmamk_f32 v82, v98, 0x3e38aa3b, v217
	v_max3_f32 v7, v80, s52, v81
	v_fmamk_f32 v83, v99, 0x3e38aa3b, v218
	v_fmamk_f32 v84, v100, 0x3e38aa3b, v219
	v_max3_f32 v7, v7, v82, v83
	v_fmamk_f32 v85, v101, 0x3e38aa3b, v220
	v_add3_u32 v6, v188, s58, 32
	v_fmamk_f32 v86, v102, 0x3e38aa3b, v221
	v_max3_f32 v7, v7, v84, v85
	v_fmamk_f32 v87, v103, 0x3e38aa3b, v222
	v_cvt_f32_i32_e32 v6, v6
	v_fmamk_f32 v88, v104, 0x3e38aa3b, v223
	v_max3_f32 v7, v7, v86, v87
	v_fmamk_f32 v89, v105, 0x3e38aa3b, v224
	v_fmamk_f32 v90, v106, 0x3e38aa3b, v225
	v_max3_f32 v7, v7, v88, v89
	v_fmamk_f32 v91, v107, 0x3e38aa3b, v226
	v_fmamk_f32 v92, v108, 0x3e38aa3b, v227
	v_max3_f32 v7, v7, v90, v91
	v_fmamk_f32 v93, v109, 0x3e38aa3b, v228
	v_fmamk_f32 v94, v110, 0x3e38aa3b, v229
	v_max3_f32 v7, v7, v92, v93
	v_fmamk_f32 v95, v111, 0x3e38aa3b, v230
	v_mul_f32_e64 v6, -v214, v6
	v_max3_f32 v7, v7, v94, v95
	s_mov_b64 s[8:9], 0

.LBB0_379:
	v_sub_f32_e32 v6, v246, v6
	v_sub_f32_e32 v7, v80, v6
	v_exp_f32_e32 v7, v7
	v_sub_f32_e32 v9, v81, v6
	v_exp_f32_e32 v9, v9
	v_sub_f32_e32 v10, v82, v6
	v_exp_f32_e32 v10, v10
	v_sub_f32_e32 v11, v83, v6
	v_exp_f32_e32 v11, v11
	v_sub_f32_e32 v12, v84, v6
	v_add_f32_e32 v8, 0, v7
	v_exp_f32_e32 v12, v12
	v_sub_f32_e32 v13, v85, v6
	v_add_f32_e32 v8, v9, v8
	v_exp_f32_e32 v13, v13
	v_sub_f32_e32 v14, v86, v6
	v_add_f32_e32 v8, v10, v8
	v_exp_f32_e32 v14, v14
	v_sub_f32_e32 v15, v87, v6
	v_add_f32_e32 v8, v11, v8
	v_exp_f32_e32 v15, v15
	v_sub_f32_e32 v80, v88, v6
	v_add_f32_e32 v8, v12, v8
	v_exp_f32_e32 v80, v80
	v_sub_f32_e32 v81, v89, v6
	v_add_f32_e32 v8, v13, v8
	v_exp_f32_e32 v81, v81
	v_sub_f32_e32 v82, v90, v6
	v_add_f32_e32 v8, v14, v8
	v_exp_f32_e32 v82, v82
	v_sub_f32_e32 v83, v91, v6
	v_add_f32_e32 v8, v15, v8
	v_exp_f32_e32 v83, v83
	v_add_f32_e32 v8, v80, v8
	v_add_f32_e32 v8, v81, v8
	v_sub_f32_e32 v84, v92, v6
	v_sub_f32_e32 v85, v93, v6
	v_sub_f32_e32 v86, v94, v6
	v_sub_f32_e32 v6, v95, v6
	v_add_f32_e32 v8, v82, v8
	v_exp_f32_e32 v87, v6
	v_cvt_pk_bf16_f32 v6, v7, v9
	v_cvt_pk_bf16_f32 v9, v14, v15
	v_add_f32_e32 v8, v83, v8
	v_cvt_pk_bf16_f32 v7, v10, v11
	v_cvt_pk_bf16_f32 v10, v80, v81
	v_cvt_pk_bf16_f32 v11, v82, v83
	v_exp_f32_e32 v84, v84
	v_exp_f32_e32 v85, v85
	v_exp_f32_e32 v86, v86
	v_add_f32_e32 v8, v84, v8
	v_add_f32_e32 v8, v85, v8
	v_add_f32_e32 v8, v86, v8
	v_add_f32_e32 v88, v87, v8
	v_cvt_pk_bf16_f32 v8, v12, v13
	v_cvt_pk_bf16_f32 v12, v84, v85
	v_cvt_pk_bf16_f32 v13, v86, v87
	s_waitcnt lgkmcnt(7)
	v_mfma_f32_32x32x16_bf16 v[64:79], v[132:135], v[6:9], v[64:79]
	v_add_f32_e32 v245, v245, v88
	s_waitcnt lgkmcnt(6)
	v_mfma_f32_32x32x16_bf16 v[64:79], v[136:139], v[10:13], v[64:79]
	s_waitcnt lgkmcnt(5)
	v_mfma_f32_32x32x16_bf16 v[48:63], v[140:143], v[6:9], v[48:63]
	s_waitcnt lgkmcnt(4)
	v_mfma_f32_32x32x16_bf16 v[48:63], v[144:147], v[10:13], v[48:63]
	s_waitcnt lgkmcnt(3)
	v_mfma_f32_32x32x16_bf16 v[32:47], v[148:151], v[6:9], v[32:47]
	s_waitcnt lgkmcnt(2)
	v_mfma_f32_32x32x16_bf16 v[32:47], v[152:155], v[10:13], v[32:47]
	s_waitcnt lgkmcnt(1)
	v_mfma_f32_32x32x16_bf16 v[16:31], v[156:159], v[6:9], v[16:31]
	s_waitcnt lgkmcnt(0)
	v_mfma_f32_32x32x16_bf16 v[16:31], v[160:163], v[10:13], v[16:31]
	s_cmp_gt_u32 s59, s55
	s_cbranch_scc1 .LBB0_309
